# mixer rms-norm row loop: modulation-vector loads hoisted the same way as in the FFN norm (on top of v40)
# baseline (speedup 1.0000x reference)
.LBB0_191:
	s_waitcnt vmcnt(3)
	v_mul_f32_e32 v0, v31, v31
	s_waitcnt vmcnt(2)
	v_mul_f32_e32 v42, v27, v27
	v_fmac_f32_e32 v0, v30, v30
	v_fmac_f32_e32 v42, v26, v26
	v_fmac_f32_e32 v0, v32, v32
	v_fmac_f32_e32 v42, v28, v28
	v_fmac_f32_e32 v0, v33, v33
	v_fmac_f32_e32 v42, v29, v29
	s_waitcnt vmcnt(0)
	v_pk_mul_f32 v[46:47], v[18:19], v[18:19]
	v_pk_mul_f32 v[58:59], v[22:23], v[22:23]
	v_add_f32_e32 v0, v0, v42
	v_pk_mul_f32 v[42:43], v[20:21], v[20:21]
	v_pk_mul_f32 v[44:45], v[24:25], v[24:25]
	v_mov_b32_e32 v60, v46
	v_mov_b32_e32 v61, v58
	v_mov_b32_e32 v58, v47
	v_pk_add_f32 v[46:47], v[60:61], v[58:59]
	v_mov_b32_e32 v58, v42
	v_mov_b32_e32 v59, v44
	v_pk_add_f32 v[46:47], v[58:59], v[46:47]
	v_mov_b32_e32 v44, v43
	v_pk_add_f32 v[42:43], v[44:45], v[46:47]
	s_cmpk_lt_u32 s2, 0x4000
	v_add_f32_e32 v0, v43, v0
	v_add_f32_e32 v0, v42, v0
	ds_bpermute_b32 v42, v35, v0
	s_movk_i32 s0, 0x4800
	s_cselect_b32 s0, 0x2400, s0
	s_cmpk_gt_i32 s2, 0x1fff
	s_cselect_b32 s0, s0, 0
	s_waitcnt lgkmcnt(0)
	v_add_f32_e32 v0, v0, v42
	ds_bpermute_b32 v42, v48, v0
	s_lshl_b32 s0, s0, 2
	v_readlane_b32 s1, v254, 45
	s_add_u32 s0, s1, s0
	v_readlane_b32 s1, v254, 47
	s_waitcnt lgkmcnt(0)
	v_add_f32_e32 v0, v0, v42
	ds_bpermute_b32 v42, v49, v0
	s_addc_u32 s1, s1, 0
	s_add_u32 s4, s0, 0x3000
	s_addc_u32 s5, s1, 0
	s_add_u32 s6, s0, 0x4000
	s_waitcnt lgkmcnt(0)
	v_add_f32_e32 v0, v0, v42
	ds_bpermute_b32 v42, v50, v0
	s_addc_u32 s7, s1, 0
	global_load_dwordx4 v[100:103], v56, s[6:7]
	global_load_dwordx4 v[104:107], v56, s[4:5]
	global_load_dwordx4 v[108:111], v53, s[6:7]
	global_load_dwordx4 v[112:115], v53, s[4:5]
	global_load_dwordx4 v[116:119], v54, s[6:7]
	global_load_dwordx4 v[120:123], v54, s[4:5]
	global_load_dwordx4 v[124:127], v55, s[6:7]
	global_load_dwordx4 v[128:131], v55, s[4:5]
	s_waitcnt lgkmcnt(0)
	v_add_f32_e32 v0, v0, v42
	ds_bpermute_b32 v42, v51, v0
	s_waitcnt lgkmcnt(0)
	v_add_f32_e32 v0, v0, v42
	ds_bpermute_b32 v42, v52, v0
	s_waitcnt lgkmcnt(0)
	v_add_f32_e32 v0, v0, v42
	v_fmamk_f32 v0, v0, 0x3a800000, v199
	v_cmp_gt_f32_e32 vcc, s21, v0
	v_mul_f32_e32 v42, 0x4f800000, v0
	s_nop 0
	v_cndmask_b32_e32 v0, v0, v42, vcc
	v_sqrt_f32_e32 v42, v0
	s_nop 0
	v_add_u32_e32 v43, -1, v42
	v_fma_f32 v44, -v43, v42, v0
	v_cmp_ge_f32_e64 s[38:39], 0, v44
	v_add_u32_e32 v44, 1, v42
	s_nop 0
	v_cndmask_b32_e64 v43, v42, v43, s[38:39]
	v_fma_f32 v42, -v44, v42, v0
	v_cmp_lt_f32_e64 s[38:39], 0, v42
	s_nop 1
	v_cndmask_b32_e64 v42, v43, v44, s[38:39]
	v_mul_f32_e32 v43, 0x37800000, v42
	v_cndmask_b32_e32 v42, v42, v43, vcc
	v_cmp_class_f32_e32 vcc, v0, v200
	s_nop 1
	v_cndmask_b32_e32 v0, v42, v0, vcc
	v_div_scale_f32 v42, s[0:1], v0, v0, 1.0
	v_rcp_f32_e32 v43, v42
	v_readlane_b32 s0, v249, 52
	v_readlane_b32 s1, v249, 53
	s_add_u32 s2, s2, s0
	v_fma_f32 v44, -v42, v43, 1.0
	v_fmac_f32_e32 v43, v44, v43
	v_div_scale_f32 v44, vcc, 1.0, v0, 1.0
	v_mul_f32_e32 v45, v44, v43
	v_fma_f32 v46, -v42, v45, v44
	v_fmac_f32_e32 v45, v46, v43
	v_fma_f32 v42, -v42, v45, v44
	v_div_fmas_f32 v42, v42, v43, v45
	v_div_fixup_f32 v0, v42, v0, 1.0
	v_pk_mul_f32 v[30:31], v[30:31], v[0:1] op_sel_hi:[1,0]
	v_pk_mul_f32 v[32:33], v[32:33], v[0:1] op_sel_hi:[1,0]
	v_pk_mul_f32 v[30:31], v[2:3], v[30:31]
	v_pk_mul_f32 v[32:33], v[4:5], v[32:33]
	v_pk_mul_f32 v[26:27], v[26:27], v[0:1] op_sel_hi:[1,0]
	v_pk_mul_f32 v[28:29], v[28:29], v[0:1] op_sel_hi:[1,0]
	v_pk_mul_f32 v[26:27], v[6:7], v[26:27]
	v_pk_mul_f32 v[28:29], v[8:9], v[28:29]
	v_pk_mul_f32 v[22:23], v[22:23], v[0:1] op_sel_hi:[1,0]
	v_pk_mul_f32 v[24:25], v[24:25], v[0:1] op_sel_hi:[1,0]
	v_pk_mul_f32 v[22:23], v[10:11], v[22:23]
	v_pk_mul_f32 v[24:25], v[12:13], v[24:25]
	v_pk_mul_f32 v[18:19], v[18:19], v[0:1] op_sel_hi:[1,0]
	v_pk_mul_f32 v[20:21], v[20:21], v[0:1] op_sel_hi:[1,0]
	v_pk_mul_f32 v[18:19], v[18:19], v[14:15]
	v_pk_mul_f32 v[20:21], v[20:21], v[16:17]
	s_addc_u32 s3, s3, s1
	v_readlane_b32 s0, v253, 22
	v_readlane_b32 s1, v253, 23
	s_cmpk_gt_i32 s2, 0x41ff
	s_waitcnt vmcnt(0)
	v_pk_add_f32 v[42:43], v[100:101], 1.0 op_sel_hi:[1,0]
	s_nop 0
	v_pk_fma_f32 v[30:31], v[42:43], v[30:31], v[104:105]
	v_pk_add_f32 v[42:43], v[102:103], 1.0 op_sel_hi:[1,0]
	v_cvt_pk_bf16_f32 v30, v30, v31
	v_pk_fma_f32 v[32:33], v[42:43], v[32:33], v[106:107]
	s_nop 0
	v_cvt_pk_bf16_f32 v31, v32, v33
	global_store_dwordx2 v[40:41], v[30:31], off
	v_pk_add_f32 v[30:31], v[108:109], 1.0 op_sel_hi:[1,0]
	s_nop 0
	v_pk_fma_f32 v[26:27], v[30:31], v[26:27], v[112:113]
	v_pk_add_f32 v[30:31], v[110:111], 1.0 op_sel_hi:[1,0]
	v_cvt_pk_bf16_f32 v26, v26, v27
	v_pk_fma_f32 v[28:29], v[30:31], v[28:29], v[114:115]
	s_nop 0
	v_cvt_pk_bf16_f32 v27, v28, v29
	global_store_dwordx2 v[40:41], v[26:27], off offset:512
	v_pk_add_f32 v[26:27], v[116:117], 1.0 op_sel_hi:[1,0]
	s_nop 0
	v_pk_fma_f32 v[22:23], v[22:23], v[26:27], v[120:121]
	v_pk_add_f32 v[26:27], v[118:119], 1.0 op_sel_hi:[1,0]
	v_cvt_pk_bf16_f32 v22, v22, v23
	v_pk_fma_f32 v[24:25], v[24:25], v[26:27], v[122:123]
	s_nop 0
	v_cvt_pk_bf16_f32 v23, v24, v25
	global_store_dwordx2 v[40:41], v[22:23], off offset:1024
	v_pk_add_f32 v[26:27], v[124:125], 1.0 op_sel_hi:[1,0]
	s_nop 0
	v_pk_fma_f32 v[18:19], v[18:19], v[26:27], v[128:129]
	v_pk_add_f32 v[22:23], v[126:127], 1.0 op_sel_hi:[1,0]
	v_cvt_pk_bf16_f32 v18, v18, v19
	v_pk_fma_f32 v[20:21], v[20:21], v[22:23], v[130:131]
	s_nop 0
	v_cvt_pk_bf16_f32 v19, v20, v21
	global_store_dwordx2 v[40:41], v[18:19], off offset:1536
	v_lshl_add_u64 v[40:41], v[40:41], 0, s[0:1]
	s_cbranch_scc1 .LBB0_194
